# k52 + DSA insert tails with lo-half list counts in SGPRs (5 VALU per tail instead of 7) + two-phase exact final cut
# speedup vs baseline: 1.0016x; 1.0002x over previous
; #define LAS __attribute__((address_space(3)))
; DI float bflo(unsigned w) { return __uint_as_float(w << 16); }
; DI float bfhi(unsigned w) { return __uint_as_float(w & 0xffff0000u); }
; #define DSA_LOADT(R, tile) do { _Pragma("unroll") for (int i_ = 0; i_ < 2; ++i_) R[i_] = *(const u32x4*)(kglob + (size_t)((tile) * KT_KEYS + kc0 + 64 * i_) * 64 + kp0 * 8); } while (0)
; #define DSA_STORET(R, bufi) do { _Pragma("unroll") for (int i_ = 0; i_ < 2; ++i_) *(LAS u32x4*)(lds + A_KT + (bufi) * KT_BYTES + (kc0 + 64 * i_) * KT_RS + kp0 * 16) = R[i_]; } while (0)
; DI void dsa_unit(const Params& p, int l, int b, int g32, LAS unsigned char* lds) {
;     ...
;   float w0[8], w1[8];
;   { const u32x4 wa = *(const u32x4*)(proj + (tq0 + 2 * h) * NP + C_WI), wb = *(const u32x4*)(proj + (tq0 + 2 * h + 1) * NP + C_WI);
; #pragma unroll
;     for (int i = 0; i < 4; ++i) { w0[2 * i] = 0.5f * bflo(wa[i]); w0[2 * i + 1] = 0.5f * bfhi(wa[i]); w1[2 * i] = 0.5f * bflo(wb[i]); w1[2 * i + 1] = 0.5f * bfhi(wb[i]); } }
;   int cnt0 = 0, cnt1 = 0, cnt2 = 0, cnt3 = 0; unsigned tau0 = 0u, tau1 = 0u, tau2 = 0u, tau3 = 0u;
;   const u16* kglob = (const u16*)(p.ws + WS_KIC) + (size_t)b * S * 64;
;   u32x4 krA[2], krB[2];
;   const int kc0 = tid >> 3, kp0 = (tid & 7);
;     ...
;   const int nstep = (end + KT_KEYS - 1) / KT_KEYS;
;     ...
;   for (int rep_ = 0; rep_ < 2; ++rep_) { cnt0 = cnt1 = cnt2 = cnt3 = 0; tau0 = tau1 = tau2 = tau3 = 0u; __syncthreads();
;     ...
;   LAS int* cflag = (LAS int*)(lds + A_KT + 2 * KT_BYTES);
;   if (tid < 3) cflag[tid] = 0;
;   DSA_LOADT(krA, 0);
;   if (nstep > 1) DSA_LOADT(krB, 1);
;   DSA_STORET(krA, 0);
;   __syncthreads();
.LBB0_367:
	v_lshlrev_b32_e32 v105, 3, v11
	s_waitcnt vmcnt(3)
	v_lshlrev_b32_e32 v11, 16, v6
	v_and_b32_e32 v6, 0xffff0000, v6
	v_mul_f32_e32 v108, 0.5, v6
	s_waitcnt vmcnt(2)
	v_lshlrev_b32_e32 v6, 16, v2
	v_and_b32_e32 v2, 0xffff0000, v2
	v_mul_f32_e32 v114, 0.5, v2
	v_lshlrev_b32_e32 v2, 16, v7
	v_mul_f32_e32 v115, 0.5, v2
	v_and_b32_e32 v2, 0xffff0000, v7
	v_mul_f32_e32 v116, 0.5, v2
	v_lshlrev_b32_e32 v2, 16, v3
	v_mul_f32_e32 v117, 0.5, v2
	v_and_b32_e32 v2, 0xffff0000, v3
	v_mul_f32_e32 v118, 0.5, v2
	v_lshlrev_b32_e32 v2, 16, v8
	v_mul_f32_e32 v119, 0.5, v2
	v_and_b32_e32 v2, 0xffff0000, v8
	v_mul_f32_e32 v120, 0.5, v2
	v_lshlrev_b32_e32 v2, 16, v4
	v_mul_f32_e32 v121, 0.5, v2
	v_and_b32_e32 v2, 0xffff0000, v4
	v_mul_f32_e32 v124, 0.5, v2
	v_lshlrev_b32_e32 v2, 16, v9
	v_mul_f32_e32 v125, 0.5, v2
	v_and_b32_e32 v2, 0xffff0000, v9
	v_mul_f32_e32 v126, 0.5, v2
	v_lshlrev_b32_e32 v2, 16, v5
	v_mul_f32_e32 v127, 0.5, v2
	v_and_b32_e32 v2, 0xffff0000, v5
	s_add_i32 s24, 0, 0x18000
	s_movk_i32 s2, 0x3000
	v_mul_f32_e32 v146, 0.5, v2
	v_add_u32_e32 v2, s24, v0
	v_mul_lo_u32 v4, v98, s59
	v_and_b32_e32 v123, 63, v103
	v_and_b32_e32 v128, 31, v103
	v_mul_lo_u32 v99, v104, s2
	s_add_i32 s2, s22, 0xbf
	v_add_u32_e32 v147, v2, v4
	v_mov_b32_e32 v2, s24
	s_lshr_b32 s25, s2, 7
	v_mad_u32_u24 v5, v128, s59, v2
	v_lshlrev_b64 v[2:3], v123, -1
	v_readlane_b32 s2, v251, 42
	v_not_b32_e32 v113, v3
	v_add_u32_e32 v129, 0, v99
	v_mov_b32_e32 v3, s2
	v_not_b32_e32 v112, v2
	v_add_u32_e32 v2, s2, v0
	v_mad_u32_u24 v3, v128, s59, v3
	v_lshlrev_b32_e32 v106, 3, v102
	s_add_i32 s23, s22, 64
	v_mul_f32_e32 v107, 0.5, v11
	v_mul_f32_e32 v109, 0.5, v6
	v_mov_b32_e32 v144, 0
	s_mov_b32 s1, 0
	v_sub_u32_e32 v148, 0, v102
	v_cmp_gt_u32_e64 s[6:7], 32, v123
	v_lshl_add_u32 v149, v123, 2, v129
	v_or_b32_e32 v138, 0x180, v123
	v_or_b32_e32 v139, 0x1c0, v123
	v_or_b32_e32 v140, 0x200, v123
	v_or_b32_e32 v141, 0x240, v123
	v_or_b32_e32 v142, 0x280, v123
	v_or_b32_e32 v143, 0x2c0, v123
	v_cmp_eq_u32_e64 s[8:9], 0, v123
	v_cmp_eq_u32_e64 s[10:11], 0, v103
	v_or_b32_e32 v150, 64, v128
	s_mov_b32 s26, 0
	s_mov_b32 s27, 0
	s_mov_b32 s29, 0
	v_add_u32_e32 v151, v5, v10
	v_add_u32_e32 v152, v2, v4
	v_add_u32_e32 v153, v3, v10
	v_mov_b32_e32 v145, 0
	s_mov_b32 s4, 0
	v_mov_b32_e32 v154, 0
	v_mov_b32_e32 v155, 0
	v_mov_b32_e32 v156, 0
	v_mov_b32_e32 v157, 0
	s_waitcnt vmcnt(1)
	ds_write_b128 v147, v[82:85]
	s_waitcnt vmcnt(0)
	ds_write_b128 v147, v[86:89] offset:9216
	s_waitcnt lgkmcnt(0)
	s_barrier

.LBB0_370:
	ds_read_b128 v[208:211], v151
	ds_read_b128 v[212:215], v151 offset:32
	ds_read_b128 v[216:219], v151 offset:4608
	ds_read_b128 v[220:223], v151 offset:4640
	ds_read_b128 v[224:227], v151 offset:9216
	ds_read_b128 v[228:231], v151 offset:9248
	ds_read_b128 v[232:235], v151 offset:13824
	ds_read_b128 v[236:239], v151 offset:13856
	s_lshl_b32 s2, s29, 7
	v_cndmask_b32_e64 v158, v155, v157, s[6:7]
	s_cmp_le_u32 s2, s22
	s_waitcnt lgkmcnt(4)
	v_mfma_f32_32x32x16_bf16 v[50:65], v[66:69], v[208:211], 0
	ds_read_b128 v[208:211], v151 offset:64
	s_cselect_b64 s[18:19], -1, 0
	v_mfma_f32_32x32x16_bf16 v[50:65], v[70:73], v[212:215], v[50:65]
	ds_read_b128 v[212:215], v151 offset:4672
	v_mfma_f32_32x32x16_bf16 v[34:49], v[66:69], v[216:219], 0
	ds_read_b128 v[216:219], v151 offset:9280
	v_mfma_f32_32x32x16_bf16 v[34:49], v[70:73], v[220:223], v[34:49]
	ds_read_b128 v[220:223], v151 offset:13888
	s_waitcnt lgkmcnt(4)
	v_mfma_f32_32x32x16_bf16 v[18:33], v[66:69], v[224:227], 0
	ds_read_b128 v[224:227], v151 offset:96
	v_mfma_f32_32x32x16_bf16 v[18:33], v[70:73], v[228:231], v[18:33]
	ds_read_b128 v[228:231], v151 offset:4704
	v_mfma_f32_32x32x16_bf16 v[2:17], v[66:69], v[232:235], 0
	ds_read_b128 v[232:235], v151 offset:9312
	v_mfma_f32_32x32x16_bf16 v[2:17], v[70:73], v[236:239], v[2:17]
	ds_read_b128 v[236:239], v151 offset:13920
	s_waitcnt lgkmcnt(4)
	v_mfma_f32_32x32x16_bf16 v[50:65], v[74:77], v[208:211], v[50:65]
	v_mfma_f32_32x32x16_bf16 v[34:49], v[74:77], v[212:215], v[34:49]
	v_mfma_f32_32x32x16_bf16 v[18:33], v[74:77], v[216:219], v[18:33]
	v_mfma_f32_32x32x16_bf16 v[2:17], v[74:77], v[220:223], v[2:17]
	s_waitcnt lgkmcnt(0)
	v_mfma_f32_32x32x16_bf16 v[50:65], v[78:81], v[224:227], v[50:65]
	v_mfma_f32_32x32x16_bf16 v[34:49], v[78:81], v[228:231], v[34:49]
	s_nop 8
	v_fma_f32 v159, v107, v50, 0
	v_fma_f32 v50, v107, |v50|, v159
	v_fmac_f32_e32 v50, v108, v51
	v_fma_f32 v50, v108, |v51|, v50
	v_fmac_f32_e32 v50, v115, v52
	v_fma_f32 v50, v115, |v52|, v50
	v_fmac_f32_e32 v50, v116, v53
	v_fma_f32 v50, v116, |v53|, v50
	v_fmac_f32_e32 v50, v119, v54
	v_fma_f32 v50, v119, |v54|, v50
	v_mfma_f32_32x32x16_bf16 v[18:33], v[78:81], v[232:235], v[18:33]
	v_fmac_f32_e32 v50, v120, v55
	v_fma_f32 v50, v120, |v55|, v50
	v_fmac_f32_e32 v50, v125, v56
	v_fma_f32 v50, v125, |v56|, v50
	v_fmac_f32_e32 v50, v126, v57
	v_fma_f32 v50, v126, |v57|, v50
	v_mfma_f32_32x32x16_bf16 v[2:17], v[78:81], v[236:239], v[2:17]
	v_ashrrev_i32_e32 v52, 31, v50
	v_or_b32_e32 v51, s2, v128
	v_bitop3_b32 v50, v52, v50, s92 bitop3:0x36
	v_and_or_b32 v50, v50, s5, v51
	v_cmp_gt_u32_e32 vcc, v50, v158
	s_and_b64 vcc, vcc, s[18:19]
	s_cbranch_vccz .LBB0_376
	s_bcnt1_i32_b32 s3, vcc_lo
	v_mbcnt_lo_u32_b32 v53, vcc_lo, 0
	s_sub_i32 s12, s26, s3
	v_mbcnt_hi_u32_b32 v53, vcc_hi, v53
	s_addk_i32 s12, 0x600
	s_sub_i32 s12, s12, s1
	s_bcnt1_i32_b32 s13, vcc_hi
	v_and_b32_e32 v54, s12, v148
	v_add3_u32 v53, v53, s1, v54
	v_lshl_add_u32 v53, v53, 2, v129
	s_mov_b64 exec, vcc
	ds_write_b32 v53, v50
	s_mov_b64 exec, -1
	s_add_i32 s1, s1, s3
	s_add_i32 s26, s13, s26
.LBB0_376:
	v_fma_f32 v50, v109, v58, 0
	v_fma_f32 v50, v109, |v58|, v50
	v_fmac_f32_e32 v50, v114, v59
	v_fma_f32 v50, v114, |v59|, v50
	v_fmac_f32_e32 v50, v117, v60
	v_fma_f32 v50, v117, |v60|, v50
	v_fmac_f32_e32 v50, v118, v61
	v_fma_f32 v50, v118, |v61|, v50
	v_fmac_f32_e32 v50, v121, v62
	v_fma_f32 v50, v121, |v62|, v50
	v_fmac_f32_e32 v50, v124, v63
	v_fma_f32 v50, v124, |v63|, v50
	v_fmac_f32_e32 v50, v127, v64
	v_fma_f32 v50, v127, |v64|, v50
	v_fmac_f32_e32 v50, v146, v65
	v_fma_f32 v52, v146, |v65|, v50
	v_ashrrev_i32_e32 v53, 31, v52
	v_bitop3_b32 v52, v53, v52, s92 bitop3:0x36
	v_cndmask_b32_e64 v50, v154, v156, s[6:7]
	v_and_or_b32 v51, v52, s5, v51
	v_cmp_gt_u32_e32 vcc, v51, v50
	s_and_b64 vcc, vcc, s[18:19]
	s_cbranch_vccz .LBB0_382
	s_bcnt1_i32_b32 s3, vcc_lo
	v_mbcnt_lo_u32_b32 v53, vcc_lo, 0
	s_sub_i32 s12, s27, s3
	v_mbcnt_hi_u32_b32 v53, vcc_hi, v53
	s_addk_i32 s12, 0x600
	s_sub_i32 s12, s12, s4
	s_bcnt1_i32_b32 s13, vcc_hi
	v_and_b32_e32 v54, s12, v148
	v_add3_u32 v53, v53, s4, v54
	v_lshl_add_u32 v53, v53, 2, v129
	s_mov_b64 exec, vcc
	ds_write_b32 v53, v51 offset:3072
	s_mov_b64 exec, -1
	s_add_i32 s4, s4, s3
	s_add_i32 s27, s13, s27
.LBB0_382:
	v_fma_f32 v51, v107, v34, 0
	v_fma_f32 v34, v107, |v34|, v51
	v_fmac_f32_e32 v34, v108, v35
	v_fma_f32 v34, v108, |v35|, v34
	v_fmac_f32_e32 v34, v115, v36
	v_fma_f32 v34, v115, |v36|, v34
	v_fmac_f32_e32 v34, v116, v37
	v_fma_f32 v34, v116, |v37|, v34
	v_fmac_f32_e32 v34, v119, v38
	v_fma_f32 v34, v119, |v38|, v34
	v_fmac_f32_e32 v34, v120, v39
	v_fma_f32 v34, v120, |v39|, v34
	v_fmac_f32_e32 v34, v125, v40
	v_fma_f32 v34, v125, |v40|, v34
	v_fmac_f32_e32 v34, v126, v41
	v_fma_f32 v35, v126, |v41|, v34
	s_or_b32 s3, s2, 32
	v_ashrrev_i32_e32 v36, 31, v35
	v_or_b32_e32 v34, s3, v128
	v_bitop3_b32 v35, v36, v35, s92 bitop3:0x36
	s_cmp_lt_u32 s3, s23
	v_and_or_b32 v35, v35, s5, v34
	s_cselect_b64 s[18:19], -1, 0
	v_cmp_gt_u32_e32 vcc, v35, v158
	s_and_b64 vcc, vcc, s[18:19]
	s_cbranch_vccz .LBB0_388
	s_bcnt1_i32_b32 s3, vcc_lo
	v_mbcnt_lo_u32_b32 v37, vcc_lo, 0
	s_sub_i32 s12, s26, s3
	v_mbcnt_hi_u32_b32 v37, vcc_hi, v37
	s_addk_i32 s12, 0x600
	s_sub_i32 s12, s12, s1
	s_bcnt1_i32_b32 s13, vcc_hi
	v_and_b32_e32 v38, s12, v148
	v_add3_u32 v37, v37, s1, v38
	v_lshl_add_u32 v37, v37, 2, v129
	s_mov_b64 exec, vcc
	ds_write_b32 v37, v35
	s_mov_b64 exec, -1
	s_add_i32 s1, s1, s3
	s_add_i32 s26, s13, s26
.LBB0_388:
	v_fma_f32 v35, v109, v42, 0
	v_fma_f32 v35, v109, |v42|, v35
	v_fmac_f32_e32 v35, v114, v43
	v_fma_f32 v35, v114, |v43|, v35
	v_fmac_f32_e32 v35, v117, v44
	v_fma_f32 v35, v117, |v44|, v35
	v_fmac_f32_e32 v35, v118, v45
	v_fma_f32 v35, v118, |v45|, v35
	v_fmac_f32_e32 v35, v121, v46
	v_fma_f32 v35, v121, |v46|, v35
	v_fmac_f32_e32 v35, v124, v47
	v_fma_f32 v35, v124, |v47|, v35
	v_fmac_f32_e32 v35, v127, v48
	v_fma_f32 v35, v127, |v48|, v35
	v_fmac_f32_e32 v35, v146, v49
	v_fma_f32 v35, v146, |v49|, v35
	v_ashrrev_i32_e32 v36, 31, v35
	v_bitop3_b32 v35, v36, v35, s92 bitop3:0x36
	v_and_or_b32 v34, v35, s5, v34
	v_cmp_gt_u32_e32 vcc, v34, v50
	s_and_b64 vcc, vcc, s[18:19]
	s_cbranch_vccz .LBB0_394
	s_bcnt1_i32_b32 s3, vcc_lo
	v_mbcnt_lo_u32_b32 v36, vcc_lo, 0
	s_sub_i32 s12, s27, s3
	v_mbcnt_hi_u32_b32 v36, vcc_hi, v36
	s_addk_i32 s12, 0x600
	s_sub_i32 s12, s12, s4
	s_bcnt1_i32_b32 s13, vcc_hi
	v_and_b32_e32 v37, s12, v148
	v_add3_u32 v36, v36, s4, v37
	v_lshl_add_u32 v36, v36, 2, v129
	s_mov_b64 exec, vcc
	ds_write_b32 v36, v34 offset:3072
	s_mov_b64 exec, -1
	s_add_i32 s4, s4, s3
	s_add_i32 s27, s13, s27
.LBB0_394:
	v_fma_f32 v34, v107, v18, 0
	v_fma_f32 v18, v107, |v18|, v34
	v_fmac_f32_e32 v18, v108, v19
	v_fma_f32 v18, v108, |v19|, v18
	v_fmac_f32_e32 v18, v115, v20
	v_fma_f32 v18, v115, |v20|, v18
	v_fmac_f32_e32 v18, v116, v21
	v_fma_f32 v18, v116, |v21|, v18
	v_fmac_f32_e32 v18, v119, v22
	v_fma_f32 v18, v119, |v22|, v18
	v_fmac_f32_e32 v18, v120, v23
	v_fma_f32 v18, v120, |v23|, v18
	v_fmac_f32_e32 v18, v125, v24
	v_fma_f32 v18, v125, |v24|, v18
	v_fmac_f32_e32 v18, v126, v25
	v_fma_f32 v19, v126, |v25|, v18
	v_ashrrev_i32_e32 v20, 31, v19
	v_or_b32_e32 v18, s2, v150
	v_bitop3_b32 v19, v20, v19, s92 bitop3:0x36
	s_cmp_lt_u32 s2, s22
	v_and_or_b32 v19, v19, s5, v18
	s_cselect_b64 s[18:19], -1, 0
	v_cmp_gt_u32_e32 vcc, v19, v158
	s_and_b64 vcc, vcc, s[18:19]
	s_cbranch_vccz .LBB0_400
	s_bcnt1_i32_b32 s3, vcc_lo
	v_mbcnt_lo_u32_b32 v21, vcc_lo, 0
	s_sub_i32 s12, s26, s3
	v_mbcnt_hi_u32_b32 v21, vcc_hi, v21
	s_addk_i32 s12, 0x600
	s_sub_i32 s12, s12, s1
	s_bcnt1_i32_b32 s13, vcc_hi
	v_and_b32_e32 v22, s12, v148
	v_add3_u32 v21, v21, s1, v22
	v_lshl_add_u32 v21, v21, 2, v129
	s_mov_b64 exec, vcc
	ds_write_b32 v21, v19
	s_mov_b64 exec, -1
	s_add_i32 s1, s1, s3
	s_add_i32 s26, s13, s26
.LBB0_400:
	v_fma_f32 v19, v109, v26, 0
	v_fma_f32 v19, v109, |v26|, v19
	v_fmac_f32_e32 v19, v114, v27
	v_fma_f32 v19, v114, |v27|, v19
	v_fmac_f32_e32 v19, v117, v28
	v_fma_f32 v19, v117, |v28|, v19
	v_fmac_f32_e32 v19, v118, v29
	v_fma_f32 v19, v118, |v29|, v19
	v_fmac_f32_e32 v19, v121, v30
	v_fma_f32 v19, v121, |v30|, v19
	v_fmac_f32_e32 v19, v124, v31
	v_fma_f32 v19, v124, |v31|, v19
	v_fmac_f32_e32 v19, v127, v32
	v_fma_f32 v19, v127, |v32|, v19
	v_fmac_f32_e32 v19, v146, v33
	v_fma_f32 v19, v146, |v33|, v19
	v_ashrrev_i32_e32 v20, 31, v19
	v_bitop3_b32 v19, v20, v19, s92 bitop3:0x36
	v_and_or_b32 v18, v19, s5, v18
	v_cmp_gt_u32_e32 vcc, v18, v50
	s_and_b64 vcc, vcc, s[18:19]
	s_cbranch_vccz .LBB0_406
	s_bcnt1_i32_b32 s3, vcc_lo
	v_mbcnt_lo_u32_b32 v20, vcc_lo, 0
	s_sub_i32 s12, s27, s3
	v_mbcnt_hi_u32_b32 v20, vcc_hi, v20
	s_addk_i32 s12, 0x600
	s_sub_i32 s12, s12, s4
	s_bcnt1_i32_b32 s13, vcc_hi
	v_and_b32_e32 v21, s12, v148
	v_add3_u32 v20, v20, s4, v21
	v_lshl_add_u32 v20, v20, 2, v129
	s_mov_b64 exec, vcc
	ds_write_b32 v20, v18 offset:3072
	s_mov_b64 exec, -1
	s_add_i32 s4, s4, s3
	s_add_i32 s27, s13, s27
.LBB0_406:
	v_fma_f32 v18, v107, v2, 0
	v_fma_f32 v2, v107, |v2|, v18
	v_fmac_f32_e32 v2, v108, v3
	v_fma_f32 v2, v108, |v3|, v2
	v_fmac_f32_e32 v2, v115, v4
	v_fma_f32 v2, v115, |v4|, v2
	v_fmac_f32_e32 v2, v116, v5
	v_fma_f32 v2, v116, |v5|, v2
	v_fmac_f32_e32 v2, v119, v6
	v_fma_f32 v2, v119, |v6|, v2
	v_fmac_f32_e32 v2, v120, v7
	v_fma_f32 v2, v120, |v7|, v2
	v_fmac_f32_e32 v2, v125, v8
	v_fma_f32 v2, v125, |v8|, v2
	v_fmac_f32_e32 v2, v126, v9
	v_fma_f32 v3, v126, |v9|, v2
	s_or_b32 s2, s2, 0x60
	v_ashrrev_i32_e32 v4, 31, v3
	v_or_b32_e32 v2, s2, v128
	v_bitop3_b32 v3, v4, v3, s92 bitop3:0x36
	s_cmp_lt_u32 s2, s23
	v_and_or_b32 v3, v3, s5, v2
	s_cselect_b64 s[18:19], -1, 0
	v_cmp_gt_u32_e32 vcc, v3, v158
	s_and_b64 vcc, vcc, s[18:19]
	s_cbranch_vccz .LBB0_412
	s_bcnt1_i32_b32 s3, vcc_lo
	v_mbcnt_lo_u32_b32 v5, vcc_lo, 0
	s_sub_i32 s12, s26, s3
	v_mbcnt_hi_u32_b32 v5, vcc_hi, v5
	s_addk_i32 s12, 0x600
	s_sub_i32 s12, s12, s1
	s_bcnt1_i32_b32 s13, vcc_hi
	v_and_b32_e32 v6, s12, v148
	v_add3_u32 v5, v5, s1, v6
	v_lshl_add_u32 v5, v5, 2, v129
	s_mov_b64 exec, vcc
	ds_write_b32 v5, v3
	s_mov_b64 exec, -1
	s_add_i32 s1, s1, s3
	s_add_i32 s26, s13, s26
.LBB0_412:
	v_fma_f32 v3, v109, v10, 0
	v_fma_f32 v3, v109, |v10|, v3
	v_fmac_f32_e32 v3, v114, v11
	v_fma_f32 v3, v114, |v11|, v3
	v_fmac_f32_e32 v3, v117, v12
	v_fma_f32 v3, v117, |v12|, v3
	v_fmac_f32_e32 v3, v118, v13
	v_fma_f32 v3, v118, |v13|, v3
	v_fmac_f32_e32 v3, v121, v14
	v_fma_f32 v3, v121, |v14|, v3
	v_fmac_f32_e32 v3, v124, v15
	v_fma_f32 v3, v124, |v15|, v3
	v_fmac_f32_e32 v3, v127, v16
	v_fma_f32 v3, v127, |v16|, v3
	v_fmac_f32_e32 v3, v146, v17
	v_fma_f32 v3, v146, |v17|, v3
	v_ashrrev_i32_e32 v4, 31, v3
	v_bitop3_b32 v3, v4, v3, s92 bitop3:0x36
	v_and_or_b32 v2, v3, s5, v2
	v_cmp_gt_u32_e32 vcc, v2, v50
	s_and_b64 vcc, vcc, s[18:19]
	s_cbranch_vccz .LBB0_418
	s_bcnt1_i32_b32 s3, vcc_lo
	v_mbcnt_lo_u32_b32 v4, vcc_lo, 0
	s_sub_i32 s12, s27, s3
	v_mbcnt_hi_u32_b32 v4, vcc_hi, v4
	s_addk_i32 s12, 0x600
	s_sub_i32 s12, s12, s4
	s_bcnt1_i32_b32 s13, vcc_hi
	v_and_b32_e32 v5, s12, v148
	v_add3_u32 v4, v4, s4, v5
	v_lshl_add_u32 v4, v4, 2, v129
	s_mov_b64 exec, vcc
	ds_write_b32 v4, v2 offset:3072
	s_mov_b64 exec, -1
	s_add_i32 s4, s4, s3
	s_add_i32 s27, s13, s27
.LBB0_418:
	v_mov_b32_e32 v144, s1
	v_mov_b32_e32 v145, s4
	v_cmp_lt_i32_e32 vcc, s88, v144
	s_and_saveexec_b64 s[12:13], vcc
	s_cbranch_execz .LBB0_482
	v_readfirstlane_b32 s2, v144
	v_readfirstlane_b32 s3, v129
	s_movk_i32 s31, 0x110
	s_mov_b32 m0, 0
	s_branch .Lmy_cut
.Lmy_cut_ret_0:
	v_mov_b32_e32 v144, s2
	s_mov_b32 s1, s2
	v_mov_b32_e32 v157, s98
	s_or_b64 exec, exec, s[12:13]
	v_cmp_lt_i32_e32 vcc, s88, v145
	s_and_saveexec_b64 s[12:13], vcc
	s_cbranch_execnz .LBB0_483

.Lmy_cut_ret_2:
	v_mov_b32_e32 v145, s2
	s_mov_b32 s4, s2
	v_mov_b32_e32 v156, s98
	s_or_b64 exec, exec, s[12:13]
	s_cmpk_lt_i32 s26, 0x281
	s_cbranch_scc0 .LBB0_451

.LBB0_551:
	ds_read_b128 v[208:211], v153
	ds_read_b128 v[212:215], v153 offset:32
	ds_read_b128 v[216:219], v153 offset:4608
	ds_read_b128 v[220:223], v153 offset:4640
	ds_read_b128 v[224:227], v153 offset:9216
	ds_read_b128 v[228:231], v153 offset:9248
	ds_read_b128 v[232:235], v153 offset:13824
	ds_read_b128 v[236:239], v153 offset:13856
	s_lshl_b32 s2, s2, 7
	v_cndmask_b32_e64 v158, v155, v157, s[6:7]
	s_cmp_le_u32 s2, s22
	s_waitcnt lgkmcnt(4)
	v_mfma_f32_32x32x16_bf16 v[50:65], v[66:69], v[208:211], 0
	ds_read_b128 v[208:211], v153 offset:64
	s_cselect_b64 s[18:19], -1, 0
	v_mfma_f32_32x32x16_bf16 v[50:65], v[70:73], v[212:215], v[50:65]
	ds_read_b128 v[212:215], v153 offset:4672
	v_mfma_f32_32x32x16_bf16 v[34:49], v[66:69], v[216:219], 0
	ds_read_b128 v[216:219], v153 offset:9280
	v_mfma_f32_32x32x16_bf16 v[34:49], v[70:73], v[220:223], v[34:49]
	ds_read_b128 v[220:223], v153 offset:13888
	s_waitcnt lgkmcnt(4)
	v_mfma_f32_32x32x16_bf16 v[18:33], v[66:69], v[224:227], 0
	ds_read_b128 v[224:227], v153 offset:96
	v_mfma_f32_32x32x16_bf16 v[18:33], v[70:73], v[228:231], v[18:33]
	ds_read_b128 v[228:231], v153 offset:4704
	v_mfma_f32_32x32x16_bf16 v[2:17], v[66:69], v[232:235], 0
	ds_read_b128 v[232:235], v153 offset:9312
	v_mfma_f32_32x32x16_bf16 v[2:17], v[70:73], v[236:239], v[2:17]
	ds_read_b128 v[236:239], v153 offset:13920
	s_waitcnt lgkmcnt(4)
	v_mfma_f32_32x32x16_bf16 v[50:65], v[74:77], v[208:211], v[50:65]
	v_mfma_f32_32x32x16_bf16 v[34:49], v[74:77], v[212:215], v[34:49]
	v_mfma_f32_32x32x16_bf16 v[18:33], v[74:77], v[216:219], v[18:33]
	v_mfma_f32_32x32x16_bf16 v[2:17], v[74:77], v[220:223], v[2:17]
	s_waitcnt lgkmcnt(0)
	v_mfma_f32_32x32x16_bf16 v[50:65], v[78:81], v[224:227], v[50:65]
	v_mfma_f32_32x32x16_bf16 v[34:49], v[78:81], v[228:231], v[34:49]
	s_nop 8
	v_fma_f32 v159, v107, v50, 0
	v_fma_f32 v50, v107, |v50|, v159
	v_fmac_f32_e32 v50, v108, v51
	v_fma_f32 v50, v108, |v51|, v50
	v_fmac_f32_e32 v50, v115, v52
	v_fma_f32 v50, v115, |v52|, v50
	v_fmac_f32_e32 v50, v116, v53
	v_fma_f32 v50, v116, |v53|, v50
	v_fmac_f32_e32 v50, v119, v54
	v_fma_f32 v50, v119, |v54|, v50
	v_mfma_f32_32x32x16_bf16 v[18:33], v[78:81], v[232:235], v[18:33]
	v_fmac_f32_e32 v50, v120, v55
	v_fma_f32 v50, v120, |v55|, v50
	v_fmac_f32_e32 v50, v125, v56
	v_fma_f32 v50, v125, |v56|, v50
	v_fmac_f32_e32 v50, v126, v57
	v_fma_f32 v50, v126, |v57|, v50
	v_mfma_f32_32x32x16_bf16 v[2:17], v[78:81], v[236:239], v[2:17]
	v_ashrrev_i32_e32 v52, 31, v50
	v_or_b32_e32 v51, s2, v128
	v_bitop3_b32 v50, v52, v50, s92 bitop3:0x36
	v_and_or_b32 v50, v50, s5, v51
	v_cmp_gt_u32_e32 vcc, v50, v158
	s_and_b64 vcc, vcc, s[18:19]
	s_cbranch_vccz .LBB0_557
	s_bcnt1_i32_b32 s3, vcc_lo
	v_mbcnt_lo_u32_b32 v53, vcc_lo, 0
	s_sub_i32 s12, s26, s3
	v_mbcnt_hi_u32_b32 v53, vcc_hi, v53
	s_addk_i32 s12, 0x600
	s_sub_i32 s12, s12, s1
	s_bcnt1_i32_b32 s13, vcc_hi
	v_and_b32_e32 v54, s12, v148
	v_add3_u32 v53, v53, s1, v54
	v_lshl_add_u32 v53, v53, 2, v129
	s_mov_b64 exec, vcc
	ds_write_b32 v53, v50
	s_mov_b64 exec, -1
	s_add_i32 s1, s1, s3
	s_add_i32 s26, s13, s26

.LBB0_599:
	v_mov_b32_e32 v144, s1
	v_mov_b32_e32 v145, s4
	v_cmp_lt_i32_e32 vcc, s88, v144
	s_and_saveexec_b64 s[12:13], vcc
	s_cbranch_execz .LBB0_752
	v_readfirstlane_b32 s2, v144
	v_readfirstlane_b32 s3, v129
	s_movk_i32 s31, 0x110
	s_mov_b32 m0, 4
	s_branch .Lmy_cut

.Lmy_cut_ret_6:
	v_mov_b32_e32 v144, s2
	s_mov_b32 s1, s2
	v_mov_b32_e32 v157, s98
	s_or_b64 exec, exec, s[12:13]
	v_cmp_lt_i32_e32 vcc, s84, v145
	s_and_saveexec_b64 s[12:13], vcc
	s_cbranch_execnz .LBB0_817

.Lmy_cut_ret_10:
	v_mov_b32_e32 v145, s2
	s_mov_b32 s4, s2
	v_mov_b32_e32 v156, s98
	s_or_b64 exec, exec, s[12:13]
	s_cmpk_lt_i32 s26, 0x191
	s_cbranch_scc0 .LBB0_711

; #define LAS __attribute__((address_space(3)))
; DI void wave_sync() { __builtin_amdgcn_fence(__ATOMIC_RELEASE, "wavefront"); __builtin_amdgcn_wave_barrier(); __builtin_amdgcn_fence(__ATOMIC_ACQUIRE, "wavefront"); }
; template <int LIM> DI int topk_cut(LAS unsigned* cand, int cnt, unsigned& tauq, int lane) {
;   if (cnt <= 256) return cnt;
;   wave_sync();
;   constexpr int NE = A_CAP / 64;
;   unsigned e[NE];
; #pragma unroll
;   for (int i = 0; i < NE; ++i) { const int j = lane + 64 * i; e[i] = j < cnt ? cand[j] : 0u; }
;   const unsigned ref = __builtin_amdgcn_readfirstlane(e[0]);
;   unsigned df = 0u;
; #pragma unroll
;   for (int i = 0; i < NE; ++i) df |= (lane + 64 * i < cnt) ? (e[i] ^ ref) : 0u;
;   df |= __shfl_xor(df, 1); df |= __shfl_xor(df, 2); df |= __shfl_xor(df, 4); df |= __shfl_xor(df, 8); df |= __shfl_xor(df, 16); df |= __shfl_xor(df, 32);
;   df = __builtin_amdgcn_readfirstlane(df);
;   const int hb = 31 - __builtin_clz(df | 1u);
;   unsigned V = hb >= 31 ? 0u : (ref & ~((2u << hb) - 1u));
; #pragma unroll 1
;     ...
;     const unsigned cv = V | (1u << bit); int c = 0;
; #pragma unroll
;     for (int i = 0; i < NE; ++i) c += __popcll(__ballot(e[i] >= cv));
;     if (c >= 256) V = cv;
;     if (c >= 256 && c <= LIM) break;
;   }
.Lmy_cutf:
	v_lshl_add_u32 v17, v123, 2, s3
	ds_read2st64_b32 v[2:3], v17 offset1:1
	ds_read2st64_b32 v[4:5], v17 offset0:2 offset1:3
	ds_read2st64_b32 v[6:7], v17 offset0:4 offset1:5
	ds_read2st64_b32 v[8:9], v17 offset0:6 offset1:7
	ds_read2st64_b32 v[10:11], v17 offset0:8 offset1:9
	ds_read2st64_b32 v[12:13], v17 offset0:10 offset1:11
	v_or_b32_e32 v14, 0x100, v123
	v_or_b32_e32 v15, 0x140, v123
	s_mov_b32 s32, s2
	s_mov_b32 s101, 0
	s_cmpk_le_u32 s2, 0x240
	s_cselect_b32 s18, 0x100, 0
	s_or_b32 m0, m0, s18
	s_waitcnt lgkmcnt(0)
	v_readfirstlane_b32 s98, v2
	v_cmp_gt_u32_e64 s[18:19], s2, v14
	v_cmp_gt_u32_e64 s[20:21], s2, v15
	v_xor_b32_e32 v16, s98, v2
	v_xor_b32_e32 v17, s98, v3
	v_xor_b32_e32 v14, s98, v4
	v_or3_b32 v16, v16, v17, v14
	v_xor_b32_e32 v17, s98, v5
	v_or_b32_e32 v16, v16, v17
	v_xor_b32_e32 v15, s98, v6
	v_cndmask_b32_e64 v15, 0, v15, s[18:19]
	v_or_b32_e32 v16, v16, v15
	v_cndmask_b32_e64 v6, 0, v6, s[18:19]
	v_xor_b32_e32 v15, s98, v7
	v_cndmask_b32_e64 v15, 0, v15, s[20:21]
	v_or_b32_e32 v16, v16, v15
	v_cndmask_b32_e64 v7, 0, v7, s[20:21]
	v_cmp_gt_u32_e64 s[18:19], s2, v138
	v_cmp_gt_u32_e64 s[20:21], s2, v139
	v_cmp_gt_u32_e32 vcc, s2, v140
	s_nop 0
	v_xor_b32_e32 v15, s98, v8
	v_cndmask_b32_e64 v15, 0, v15, s[18:19]
	v_or_b32_e32 v16, v16, v15
	v_cndmask_b32_e64 v8, 0, v8, s[18:19]
	v_xor_b32_e32 v15, s98, v9
	v_cndmask_b32_e64 v15, 0, v15, s[20:21]
	v_or_b32_e32 v16, v16, v15
	v_cndmask_b32_e64 v9, 0, v9, s[20:21]
	v_xor_b32_e32 v15, s98, v10
	v_cndmask_b32_e32 v15, 0, v15, vcc
	v_or_b32_e32 v16, v16, v15
	v_cndmask_b32_e32 v10, 0, v10, vcc
	s_bitcmp1_b32 m0, 8
	s_cbranch_scc1 .Lmy_cutf_v_skip
	v_cmp_gt_u32_e64 s[18:19], s2, v141
	v_cmp_gt_u32_e64 s[20:21], s2, v142
	v_cmp_gt_u32_e32 vcc, s2, v143
	s_nop 0
	v_xor_b32_e32 v15, s98, v11
	v_cndmask_b32_e64 v15, 0, v15, s[18:19]
	v_or_b32_e32 v16, v16, v15
	v_cndmask_b32_e64 v11, 0, v11, s[18:19]
	v_xor_b32_e32 v15, s98, v12
	v_cndmask_b32_e64 v15, 0, v15, s[20:21]
	v_or_b32_e32 v16, v16, v15
	v_cndmask_b32_e64 v12, 0, v12, s[20:21]
	v_xor_b32_e32 v15, s98, v13
	v_cndmask_b32_e32 v15, 0, v15, vcc
	v_or_b32_e32 v16, v16, v15
	v_cndmask_b32_e32 v13, 0, v13, vcc
.Lmy_cutf_v_skip:
	s_nop 1
	v_or_b32_dpp v16, v16, v16 row_ror:1 row_mask:0xf bank_mask:0xf
	s_nop 1
	v_or_b32_dpp v16, v16, v16 row_ror:2 row_mask:0xf bank_mask:0xf
	s_nop 1
	v_or_b32_dpp v16, v16, v16 row_ror:4 row_mask:0xf bank_mask:0xf
	s_nop 1
	v_or_b32_dpp v16, v16, v16 row_ror:8 row_mask:0xf bank_mask:0xf
	s_nop 1
	v_readlane_b32 s18, v16, 0
	v_readlane_b32 s19, v16, 16
	v_readlane_b32 s20, v16, 32
	v_readlane_b32 s21, v16, 48
	s_or_b32 s18, s18, s19
	s_or_b32 s20, s20, s21
	s_or_b32 s18, s18, s20
	s_or_b32 s18, s18, 1
	s_flbit_i32_b32 s18, s18
	s_sub_i32 s99, 31, s18
	s_lshl_b32 s19, -2, s99
	s_and_b32 s98, s98, s19
.Lmy_cutf_loop:
	s_lshl_b32 s100, 1, s99
	s_or_b32 s100, s98, s100
	v_cmp_ge_u32_e64 s[18:19], v2, s100
	v_cmp_ge_u32_e64 s[20:21], v3, s100
	v_cmp_le_u32_e32 vcc, s100, v4
	s_bcnt1_i32_b64 s18, s[18:19]
	s_bcnt1_i32_b64 s20, s[20:21]
	s_bcnt1_i32_b64 s19, vcc
	s_add_i32 s2, s18, s20
	s_add_i32 s2, s2, s19
	v_cmp_ge_u32_e64 s[18:19], v5, s100
	v_cmp_ge_u32_e64 s[20:21], v6, s100
	v_cmp_le_u32_e32 vcc, s100, v7
	s_bcnt1_i32_b64 s18, s[18:19]
	s_bcnt1_i32_b64 s20, s[20:21]
	s_bcnt1_i32_b64 s19, vcc
	s_add_i32 s2, s2, s18
	s_add_i32 s2, s2, s20
	s_add_i32 s2, s2, s19
	v_cmp_ge_u32_e64 s[18:19], v8, s100
	v_cmp_ge_u32_e64 s[20:21], v9, s100
	v_cmp_le_u32_e32 vcc, s100, v10
	s_bcnt1_i32_b64 s18, s[18:19]
	s_bcnt1_i32_b64 s20, s[20:21]
	s_bcnt1_i32_b64 s19, vcc
	s_add_i32 s2, s2, s18
	s_add_i32 s2, s2, s20
	s_add_i32 s2, s2, s19
	s_bitcmp1_b32 m0, 8
	s_cbranch_scc1 .Lmy_cutf_l_skip
	v_cmp_ge_u32_e64 s[18:19], v11, s100
	v_cmp_ge_u32_e64 s[20:21], v12, s100
	v_cmp_le_u32_e32 vcc, s100, v13
	s_bcnt1_i32_b64 s18, s[18:19]
	s_bcnt1_i32_b64 s20, s[20:21]
	s_bcnt1_i32_b64 s19, vcc
	s_add_i32 s2, s2, s18
	s_add_i32 s2, s2, s20
	s_add_i32 s2, s2, s19
.Lmy_cutf_l_skip:
	s_cmp_ge_u32 s2, 0x100
	s_cselect_b32 s98, s100, s98
	s_cselect_b32 s32, s2, s32
	s_cselect_b32 s101, s101, s2
	s_cbranch_scc0 .Lmy_cutf_next
	s_cmp_le_u32 s2, s31
	s_cbranch_scc1 .Lmy_cutf_done
.Lmy_cutf_next:
	s_add_i32 s99, s99, -1
	s_cmp_lt_i32 s99, 2
	s_cbranch_scc1 .Lmy_cutf_tail
	s_sub_i32 s18, s32, s101
	s_cmpk_gt_u32 s18, 0x80
	s_cbranch_scc1 .Lmy_cutf_loop
	s_cmp_eq_u32 s98, 0
	s_cbranch_scc1 .Lmy_cutf_loop
; template <int LIM> DI int topk_cut(LAS unsigned* cand, int cnt, unsigned& tauq, int lane) {
;     ...
; #pragma unroll 1
;     ...
;     const unsigned cv = V | (1u << bit); int c = 0;
; #pragma unroll
;     for (int i = 0; i < NE; ++i) c += __popcll(__ballot(e[i] >= cv));
;     if (c >= 256) V = cv;
;     if (c >= 256 && c <= LIM) break;
;   }
	v_lshrrev_b32_e32 v14, 6, v168
	s_lshl_b32 s100, 2, s99
	v_readfirstlane_b32 s2, v14
	s_mul_i32 s2, s2, 0x3c0
	s_add_i32 s2, s2, 0x21020
	v_lshl_add_u32 v16, v123, 2, s2
	ds_write2st64_b32 v16, v1, v1 offset1:1
	v_xor_b32_e32 v14, s98, v2
	v_xor_b32_e32 v15, s98, v3
	v_xor_b32_e32 v17, s98, v4
	v_cmp_gt_u32_e64 s[18:19], s100, v14
	v_cmp_gt_u32_e64 s[20:21], s100, v15
	v_cmp_gt_u32_e32 vcc, s100, v17
	s_nop 0
	s_mov_b64 exec, s[18:19]
	v_mbcnt_lo_u32_b32 v14, s18, 0
	v_mbcnt_hi_u32_b32 v14, s19, v14
	v_lshl_add_u32 v14, v14, 2, s2
	ds_write_b32 v14, v2
	s_bcnt1_i32_b64 s18, s[18:19]
	s_lshl2_add_u32 s2, s18, s2
	s_mov_b64 exec, s[20:21]
	v_mbcnt_lo_u32_b32 v14, s20, 0
	v_mbcnt_hi_u32_b32 v14, s21, v14
	v_lshl_add_u32 v14, v14, 2, s2
	ds_write_b32 v14, v3
	s_bcnt1_i32_b64 s20, s[20:21]
	s_lshl2_add_u32 s2, s20, s2
	s_mov_b64 exec, vcc
	v_mbcnt_lo_u32_b32 v14, vcc_lo, 0
	v_mbcnt_hi_u32_b32 v14, vcc_hi, v14
	v_lshl_add_u32 v14, v14, 2, s2
	ds_write_b32 v14, v4
	s_bcnt1_i32_b64 vcc_lo, vcc
	s_lshl2_add_u32 s2, vcc_lo, s2
	s_mov_b64 exec, -1
	v_xor_b32_e32 v14, s98, v5
	v_xor_b32_e32 v15, s98, v6
	v_xor_b32_e32 v17, s98, v7
	v_cmp_gt_u32_e64 s[18:19], s100, v14
	v_cmp_gt_u32_e64 s[20:21], s100, v15
	v_cmp_gt_u32_e32 vcc, s100, v17
	s_nop 0
	s_mov_b64 exec, s[18:19]
	v_mbcnt_lo_u32_b32 v14, s18, 0
	v_mbcnt_hi_u32_b32 v14, s19, v14
	v_lshl_add_u32 v14, v14, 2, s2
	ds_write_b32 v14, v5
	s_bcnt1_i32_b64 s18, s[18:19]
	s_lshl2_add_u32 s2, s18, s2
	s_mov_b64 exec, s[20:21]
	v_mbcnt_lo_u32_b32 v14, s20, 0
	v_mbcnt_hi_u32_b32 v14, s21, v14
	v_lshl_add_u32 v14, v14, 2, s2
	ds_write_b32 v14, v6
	s_bcnt1_i32_b64 s20, s[20:21]
	s_lshl2_add_u32 s2, s20, s2
	s_mov_b64 exec, vcc
	v_mbcnt_lo_u32_b32 v14, vcc_lo, 0
	v_mbcnt_hi_u32_b32 v14, vcc_hi, v14
	v_lshl_add_u32 v14, v14, 2, s2
	ds_write_b32 v14, v7
	s_bcnt1_i32_b64 vcc_lo, vcc
	s_lshl2_add_u32 s2, vcc_lo, s2
	s_mov_b64 exec, -1
	v_xor_b32_e32 v14, s98, v8
	v_xor_b32_e32 v15, s98, v9
	v_xor_b32_e32 v17, s98, v10
	v_cmp_gt_u32_e64 s[18:19], s100, v14
	v_cmp_gt_u32_e64 s[20:21], s100, v15
	v_cmp_gt_u32_e32 vcc, s100, v17
	s_nop 0
	s_mov_b64 exec, s[18:19]
	v_mbcnt_lo_u32_b32 v14, s18, 0
	v_mbcnt_hi_u32_b32 v14, s19, v14
	v_lshl_add_u32 v14, v14, 2, s2
	ds_write_b32 v14, v8
	s_bcnt1_i32_b64 s18, s[18:19]
	s_lshl2_add_u32 s2, s18, s2
	s_mov_b64 exec, s[20:21]
	v_mbcnt_lo_u32_b32 v14, s20, 0
	v_mbcnt_hi_u32_b32 v14, s21, v14
	v_lshl_add_u32 v14, v14, 2, s2
	ds_write_b32 v14, v9
	s_bcnt1_i32_b64 s20, s[20:21]
	s_lshl2_add_u32 s2, s20, s2
	s_mov_b64 exec, vcc
	v_mbcnt_lo_u32_b32 v14, vcc_lo, 0
	v_mbcnt_hi_u32_b32 v14, vcc_hi, v14
	v_lshl_add_u32 v14, v14, 2, s2
	ds_write_b32 v14, v10
	s_bcnt1_i32_b64 vcc_lo, vcc
	s_lshl2_add_u32 s2, vcc_lo, s2
	s_mov_b64 exec, -1
	s_bitcmp1_b32 m0, 8
	s_cbranch_scc1 .Lmy_cutf_s_skip
	v_xor_b32_e32 v14, s98, v11
	v_xor_b32_e32 v15, s98, v12
	v_xor_b32_e32 v17, s98, v13
	v_cmp_gt_u32_e64 s[18:19], s100, v14
	v_cmp_gt_u32_e64 s[20:21], s100, v15
	v_cmp_gt_u32_e32 vcc, s100, v17
	s_nop 0
	s_mov_b64 exec, s[18:19]
	v_mbcnt_lo_u32_b32 v14, s18, 0
	v_mbcnt_hi_u32_b32 v14, s19, v14
	v_lshl_add_u32 v14, v14, 2, s2
	ds_write_b32 v14, v11
	s_bcnt1_i32_b64 s18, s[18:19]
	s_lshl2_add_u32 s2, s18, s2
	s_mov_b64 exec, s[20:21]
	v_mbcnt_lo_u32_b32 v14, s20, 0
	v_mbcnt_hi_u32_b32 v14, s21, v14
	v_lshl_add_u32 v14, v14, 2, s2
	ds_write_b32 v14, v12
	s_bcnt1_i32_b64 s20, s[20:21]
	s_lshl2_add_u32 s2, s20, s2
	s_mov_b64 exec, vcc
	v_mbcnt_lo_u32_b32 v14, vcc_lo, 0
	v_mbcnt_hi_u32_b32 v14, vcc_hi, v14
	v_lshl_add_u32 v14, v14, 2, s2
	ds_write_b32 v14, v13
	s_bcnt1_i32_b64 vcc_lo, vcc
	s_lshl2_add_u32 s2, vcc_lo, s2
.Lmy_cutf_s_skip:
	s_mov_b64 exec, -1
	ds_read2st64_b32 v[14:15], v16 offset1:1
	s_waitcnt lgkmcnt(0)
; DI void wave_sync() { __builtin_amdgcn_fence(__ATOMIC_RELEASE, "wavefront"); __builtin_amdgcn_wave_barrier(); __builtin_amdgcn_fence(__ATOMIC_ACQUIRE, "wavefront"); }
; template <int LIM> DI int topk_cut(LAS unsigned* cand, int cnt, unsigned& tauq, int lane) {
;     ...
; #pragma unroll 1
;     ...
;     const unsigned cv = V | (1u << bit); int c = 0;
; #pragma unroll
;     for (int i = 0; i < NE; ++i) c += __popcll(__ballot(e[i] >= cv));
;     if (c >= 256) V = cv;
;     if (c >= 256 && c <= LIM) break;
;   }
;   int nc = 0;
; #pragma unroll
;   for (int i = 0; i < NE; ++i) {
;     const bool pr = e[i] >= V; const unsigned long long bal = __ballot(pr);
;     const int pos = nc + __popcll(bal & ((1ull << lane) - 1ull));
;     if (pr) cand[pos] = e[i];
;     nc += __popcll(bal);
;   }
;   wave_sync();
;   tauq = V;
;   return nc;
; }
.Lmy_cutf_p2:
	s_lshl_b32 s100, 1, s99
	s_or_b32 s100, s98, s100
	v_cmp_ge_u32_e64 s[18:19], v14, s100
	v_cmp_ge_u32_e64 s[20:21], v15, s100
	s_bcnt1_i32_b64 s18, s[18:19]
	s_bcnt1_i32_b64 s20, s[20:21]
	s_add_i32 s2, s101, s18
	s_add_i32 s2, s2, s20
	s_cmp_ge_u32 s2, 0x100
	s_cselect_b32 s98, s100, s98
	s_cbranch_scc0 .Lmy_cutf_p2n
	s_cmp_le_u32 s2, s31
	s_cbranch_scc1 .Lmy_cutf_done
.Lmy_cutf_p2n:
	s_add_i32 s99, s99, -1
	s_cmp_ge_i32 s99, 0
	s_cbranch_scc1 .Lmy_cutf_p2
	s_branch .Lmy_cutf_done
.Lmy_cutf_tail:
	s_cmp_ge_i32 s99, 0
	s_cbranch_scc1 .Lmy_cutf_loop
.Lmy_cutf_done:
	s_mov_b32 s2, 0
	v_cmp_ge_u32_e64 s[18:19], v2, s98
	v_cmp_ge_u32_e64 s[20:21], v3, s98
	v_cmp_le_u32_e32 vcc, s98, v4
	s_mov_b64 exec, s[18:19]
	v_mbcnt_lo_u32_b32 v14, s18, 0
	v_mbcnt_hi_u32_b32 v14, s19, v14
	v_lshl_add_u32 v14, v14, 2, s3
	ds_write_b32 v14, v2
	s_bcnt1_i32_b64 s100, s[18:19]
	s_add_i32 s2, s2, s100
	s_lshl2_add_u32 s3, s100, s3
	s_mov_b64 exec, s[20:21]
	v_mbcnt_lo_u32_b32 v14, s20, 0
	v_mbcnt_hi_u32_b32 v14, s21, v14
	v_lshl_add_u32 v14, v14, 2, s3
	ds_write_b32 v14, v3
	s_bcnt1_i32_b64 s100, s[20:21]
	s_add_i32 s2, s2, s100
	s_lshl2_add_u32 s3, s100, s3
	s_mov_b64 exec, vcc
	v_mbcnt_lo_u32_b32 v14, vcc_lo, 0
	v_mbcnt_hi_u32_b32 v14, vcc_hi, v14
	v_lshl_add_u32 v14, v14, 2, s3
	ds_write_b32 v14, v4
	s_bcnt1_i32_b64 s100, vcc
	s_add_i32 s2, s2, s100
	s_lshl2_add_u32 s3, s100, s3
	s_mov_b64 exec, -1
	v_cmp_ge_u32_e64 s[18:19], v5, s98
	v_cmp_ge_u32_e64 s[20:21], v6, s98
	v_cmp_le_u32_e32 vcc, s98, v7
	s_mov_b64 exec, s[18:19]
	v_mbcnt_lo_u32_b32 v14, s18, 0
	v_mbcnt_hi_u32_b32 v14, s19, v14
	v_lshl_add_u32 v14, v14, 2, s3
	ds_write_b32 v14, v5
	s_bcnt1_i32_b64 s100, s[18:19]
	s_add_i32 s2, s2, s100
	s_lshl2_add_u32 s3, s100, s3
	s_mov_b64 exec, s[20:21]
	v_mbcnt_lo_u32_b32 v14, s20, 0
	v_mbcnt_hi_u32_b32 v14, s21, v14
	v_lshl_add_u32 v14, v14, 2, s3
	ds_write_b32 v14, v6
	s_bcnt1_i32_b64 s100, s[20:21]
	s_add_i32 s2, s2, s100
	s_lshl2_add_u32 s3, s100, s3
	s_mov_b64 exec, vcc
	v_mbcnt_lo_u32_b32 v14, vcc_lo, 0
	v_mbcnt_hi_u32_b32 v14, vcc_hi, v14
	v_lshl_add_u32 v14, v14, 2, s3
	ds_write_b32 v14, v7
	s_bcnt1_i32_b64 s100, vcc
	s_add_i32 s2, s2, s100
	s_lshl2_add_u32 s3, s100, s3
	s_mov_b64 exec, -1
	v_cmp_ge_u32_e64 s[18:19], v8, s98
	v_cmp_ge_u32_e64 s[20:21], v9, s98
	v_cmp_le_u32_e32 vcc, s98, v10
	s_mov_b64 exec, s[18:19]
	v_mbcnt_lo_u32_b32 v14, s18, 0
	v_mbcnt_hi_u32_b32 v14, s19, v14
	v_lshl_add_u32 v14, v14, 2, s3
	ds_write_b32 v14, v8
	s_bcnt1_i32_b64 s100, s[18:19]
	s_add_i32 s2, s2, s100
	s_lshl2_add_u32 s3, s100, s3
	s_mov_b64 exec, s[20:21]
	v_mbcnt_lo_u32_b32 v14, s20, 0
	v_mbcnt_hi_u32_b32 v14, s21, v14
	v_lshl_add_u32 v14, v14, 2, s3
	ds_write_b32 v14, v9
	s_bcnt1_i32_b64 s100, s[20:21]
	s_add_i32 s2, s2, s100
	s_lshl2_add_u32 s3, s100, s3
	s_mov_b64 exec, vcc
	v_mbcnt_lo_u32_b32 v14, vcc_lo, 0
	v_mbcnt_hi_u32_b32 v14, vcc_hi, v14
	v_lshl_add_u32 v14, v14, 2, s3
	ds_write_b32 v14, v10
	s_bcnt1_i32_b64 s100, vcc
	s_add_i32 s2, s2, s100
	s_lshl2_add_u32 s3, s100, s3
	s_mov_b64 exec, -1
	s_bitcmp1_b32 m0, 8
	s_cbranch_scc1 .Lmy_cutf_c_skip
	v_cmp_ge_u32_e64 s[18:19], v11, s98
	v_cmp_ge_u32_e64 s[20:21], v12, s98
	v_cmp_le_u32_e32 vcc, s98, v13
	s_mov_b64 exec, s[18:19]
	v_mbcnt_lo_u32_b32 v14, s18, 0
	v_mbcnt_hi_u32_b32 v14, s19, v14
	v_lshl_add_u32 v14, v14, 2, s3
	ds_write_b32 v14, v11
	s_bcnt1_i32_b64 s100, s[18:19]
	s_add_i32 s2, s2, s100
	s_lshl2_add_u32 s3, s100, s3
	s_mov_b64 exec, s[20:21]
	v_mbcnt_lo_u32_b32 v14, s20, 0
	v_mbcnt_hi_u32_b32 v14, s21, v14
	v_lshl_add_u32 v14, v14, 2, s3
	ds_write_b32 v14, v12
	s_bcnt1_i32_b64 s100, s[20:21]
	s_add_i32 s2, s2, s100
	s_lshl2_add_u32 s3, s100, s3
	s_mov_b64 exec, vcc
	v_mbcnt_lo_u32_b32 v14, vcc_lo, 0
	v_mbcnt_hi_u32_b32 v14, vcc_hi, v14
	v_lshl_add_u32 v14, v14, 2, s3
	ds_write_b32 v14, v13
	s_bcnt1_i32_b64 s100, vcc
	s_add_i32 s2, s2, s100
	s_lshl2_add_u32 s3, s100, s3
.Lmy_cutf_c_skip:
	s_mov_b64 exec, -1
	s_and_b32 m0, m0, 0xff
	s_branch .Lmy_cut_ret_12
